# P7 main loop: LDS-DMA via SGPR base + 32-bit VGPR offset (saddr form) instead of 16 v_lshl_add_u64 per iteration; on top of P5 sab-load batching
# speedup vs baseline: 1.0136x; 1.0006x over previous
; #define PG8_STAGE(bufoff, gbase, voff) do { _Pragma("unroll") for (int _i = 0; _i < 2; ++_i) \
;         __builtin_amdgcn_global_load_lds((const unsigned*)((const char*)(gbase) + (voff)[_i]), (PG8_LAS unsigned*)(lds + (bufoff) + ldsw + _i * 8192), 16, 0, 0); } while (0)
; #define PG8_LDA(dst, b, h) do { _Pragma("unroll") for (int m = 0; m < 4; ++m) _Pragma("unroll") for (int k = 0; k < 2; ++k) dst[m][k] = *(const PG8_LAS bf16x8*)(lds + PG8_SA(b, h) + aoff + m * 2048 + k * 1024); } while (0)
; #define PG8_LDB(dst, b, h) do { _Pragma("unroll") for (int n = 0; n < 2; ++n) _Pragma("unroll") for (int k = 0; k < 2; ++k) dst[n][k] = *(const PG8_LAS bf16x8*)(lds + PG8_SB(b, h) + boff + n * 2048 + k * 1024); } while (0)
; #define PG8_MMA(ai, bj, At, Bt) do { __builtin_amdgcn_s_setprio(1); _Pragma("unroll") for (int m = 0; m < 4; ++m) _Pragma("unroll") for (int n = 0; n < 2; ++n) _Pragma("unroll") for (int k = 0; k < 2; ++k) \
;         acc[ai][bj][m][n] = __builtin_amdgcn_mfma_f32_16x16x32_bf16(Bt[n][k], At[m][k], acc[ai][bj][m][n], 0, 0, 0); __builtin_amdgcn_s_setprio(0); } while (0)
; #define PG8_WAIT_V(n) asm volatile("s_waitcnt vmcnt(" #n ")" ::: "memory")
; #define PG8_WAIT_L(n) asm volatile("s_waitcnt lgkmcnt(" #n ")" ::: "memory")
; template <class Epi, class Sched, bool ALIGN_EPI = false, bool SP2 = false>
; __device__ __forceinline__ void gemm_phase(PG8_LAS unsigned char* lds, const Gemm g, const Sched& S, const Epi& E) {
;     ...
;             const bool last = (t == nt - 2);
;             const char* a1 = cA + (size_t)(t + 1) * kstep;
;             const char* a2 = last ? nA : cA + (size_t)(t + 2) * kstep; const char* b2 = last ? nB : cB + (size_t)(t + 2) * kstep;
;             const char* a3 = a2 + kstep; const char* b3 = b2 + kstep;
;             if (last && has_next) S.a_ready(nxt);
;             if constexpr (SP2) {
;             PG8_LDB(B0, 0, 0); PG8_LDB(B1, 0, 1); PG8_SCHED; PG8_LDA(At, 0, 0); PG8_STAGE(PG8_SA(1, 1), a1 + hstep, voffA);
;             PG8_WAIT_V(8); PG8_WAIT_L(0); PG8_BAR; PG8_MMA(0, 0, At, B0); PG8_MMA(0, 1, At, B1); PG8_BAR; PG8_SCHED;
;             PG8_LDA(At, 0, 1); PG8_STAGE(PG8_SB(0, 0), b2, voffB); PG8_STAGE(PG8_SB(0, 1), b2 + hstep, voffB); PG8_STAGE(PG8_SA(0, 0), a2, voffA);
;             PG8_WAIT_V(8); PG8_WAIT_L(0); PG8_BAR; PG8_MMA(1, 0, At, B0); PG8_MMA(1, 1, At, B1); PG8_BAR; PG8_SCHED;
.LBB0_1487:
	s_add_u32 s2, s48, 0xfff80080
	s_addc_u32 s3, s49, -1
	s_add_i32 s58, 0, 0x10000
	s_cmp_eq_u32 s57, 28
	s_cselect_b32 s51, s21, s3
	s_cselect_b32 s50, s24, s2
	s_cselect_b32 s23, s19, s56
	s_cselect_b32 s22, s25, s55
	s_add_i32 s59, 0, 0x14000
	v_add_u32_e32 v156, s58, v149
	v_add_u32_e32 v172, s59, v149
	ds_read_b128 v[140:143], v156
	ds_read_b128 v[144:147], v156 offset:1024
	ds_read_b128 v[152:155], v156 offset:2048
	ds_read_b128 v[156:159], v156 offset:3072
	ds_read_b128 v[160:163], v172
	ds_read_b128 v[164:167], v172 offset:1024
	ds_read_b128 v[168:171], v172 offset:2048
	ds_read_b128 v[172:175], v172 offset:3072
	s_add_i32 m0, s35, 0xc000
	ds_read_b128 v[176:179], v151
	ds_read_b128 v[180:183], v151 offset:1024
	ds_read_b128 v[200:203], v151 offset:2048
	ds_read_b128 v[204:207], v151 offset:3072
	ds_read_b128 v[208:211], v151 offset:4096
	ds_read_b128 v[212:215], v151 offset:5120
	ds_read_b128 v[216:219], v151 offset:6144
	ds_read_b128 v[232:235], v151 offset:7168
	global_load_lds_dwordx4 v138, s[48:49]
	s_add_i32 m0, s35, 0xe000
	s_nop 0
	global_load_lds_dwordx4 v136, s[48:49]
	s_waitcnt vmcnt(8)
	s_waitcnt lgkmcnt(0)
	s_barrier
	s_setprio 1
	s_waitcnt lgkmcnt(0)
	v_mfma_f32_16x16x32_bf16 v[126:129], v[140:143], v[176:179], v[126:129]
	v_mfma_f32_16x16x32_bf16 v[118:121], v[152:155], v[176:179], v[118:121]
	v_mfma_f32_16x16x32_bf16 v[110:113], v[140:143], v[200:203], v[110:113]
	v_mfma_f32_16x16x32_bf16 v[102:105], v[152:155], v[200:203], v[102:105]
	v_mfma_f32_16x16x32_bf16 v[94:97], v[140:143], v[208:211], v[94:97]
	v_mfma_f32_16x16x32_bf16 v[86:89], v[152:155], v[208:211], v[86:89]
	v_mfma_f32_16x16x32_bf16 v[78:81], v[140:143], v[216:219], v[78:81]
	v_mfma_f32_16x16x32_bf16 v[70:73], v[152:155], v[216:219], v[70:73]
	v_mfma_f32_16x16x32_bf16 v[126:129], v[144:147], v[180:183], v[126:129]
	v_mfma_f32_16x16x32_bf16 v[118:121], v[156:159], v[180:183], v[118:121]
	v_mfma_f32_16x16x32_bf16 v[110:113], v[144:147], v[204:207], v[110:113]
	v_mfma_f32_16x16x32_bf16 v[102:105], v[156:159], v[204:207], v[102:105]
	v_mfma_f32_16x16x32_bf16 v[94:97], v[144:147], v[212:215], v[94:97]
	v_mfma_f32_16x16x32_bf16 v[86:89], v[156:159], v[212:215], v[86:89]
	v_mfma_f32_16x16x32_bf16 v[78:81], v[144:147], v[232:235], v[78:81]
	v_mfma_f32_16x16x32_bf16 v[70:73], v[156:159], v[232:235], v[70:73]
	s_setprio 0
	s_setprio 1
	v_mfma_f32_16x16x32_bf16 v[122:125], v[160:163], v[176:179], v[122:125]
	v_mfma_f32_16x16x32_bf16 v[114:117], v[168:171], v[176:179], v[114:117]
	v_mfma_f32_16x16x32_bf16 v[106:109], v[160:163], v[200:203], v[106:109]
	v_mfma_f32_16x16x32_bf16 v[98:101], v[168:171], v[200:203], v[98:101]
	v_mfma_f32_16x16x32_bf16 v[90:93], v[160:163], v[208:211], v[90:93]
	v_mfma_f32_16x16x32_bf16 v[82:85], v[168:171], v[208:211], v[82:85]
	v_mfma_f32_16x16x32_bf16 v[74:77], v[160:163], v[216:219], v[74:77]
	v_mfma_f32_16x16x32_bf16 v[66:69], v[168:171], v[216:219], v[66:69]
	v_mfma_f32_16x16x32_bf16 v[122:125], v[164:167], v[180:183], v[122:125]
	v_mfma_f32_16x16x32_bf16 v[114:117], v[172:175], v[180:183], v[114:117]
	v_mfma_f32_16x16x32_bf16 v[106:109], v[164:167], v[204:207], v[106:109]
	v_mfma_f32_16x16x32_bf16 v[98:101], v[172:175], v[204:207], v[98:101]
	v_mfma_f32_16x16x32_bf16 v[90:93], v[164:167], v[212:215], v[90:93]
	v_mfma_f32_16x16x32_bf16 v[82:85], v[172:175], v[212:215], v[82:85]
	v_mfma_f32_16x16x32_bf16 v[74:77], v[164:167], v[232:235], v[74:77]
	v_mfma_f32_16x16x32_bf16 v[66:69], v[172:175], v[232:235], v[66:69]
	s_setprio 0
	s_barrier
	s_add_i32 s2, s58, s28
	s_mov_b32 m0, s2
	ds_read_b128 v[176:179], v151 offset:16384
	ds_read_b128 v[180:183], v151 offset:17408
	ds_read_b128 v[200:203], v151 offset:18432
	ds_read_b128 v[204:207], v151 offset:19456
	ds_read_b128 v[208:211], v151 offset:20480
	ds_read_b128 v[212:215], v151 offset:21504
	ds_read_b128 v[216:219], v151 offset:22528
	ds_read_b128 v[232:235], v151 offset:23552
	global_load_lds_dwordx4 v0, s[22:23]
	s_add_i32 m0, s2, 0x2000
	s_add_u32 s2, s22, 0x80000
	s_addc_u32 s3, s23, 0
	s_add_i32 s58, s59, s28
	global_load_lds_dwordx4 v130, s[22:23]
	s_mov_b32 m0, s58
	s_nop 0
	global_load_lds_dwordx4 v0, s[2:3]
	s_add_i32 m0, s58, 0x2000
	s_nop 0
	global_load_lds_dwordx4 v130, s[2:3]
	s_mov_b32 m0, s35
	s_nop 0
	global_load_lds_dwordx4 v134, s[50:51]
	s_mov_b32 m0, s36
	s_nop 0
	global_load_lds_dwordx4 v132, s[50:51]
	s_waitcnt vmcnt(8)
	s_waitcnt lgkmcnt(0)
	s_barrier
	s_setprio 1
	s_waitcnt lgkmcnt(0)
	v_mfma_f32_16x16x32_bf16 v[62:65], v[140:143], v[176:179], v[62:65]
	v_mfma_f32_16x16x32_bf16 v[54:57], v[152:155], v[176:179], v[54:57]
	v_mfma_f32_16x16x32_bf16 v[46:49], v[140:143], v[200:203], v[46:49]
	v_mfma_f32_16x16x32_bf16 v[38:41], v[152:155], v[200:203], v[38:41]
	v_mfma_f32_16x16x32_bf16 v[30:33], v[140:143], v[208:211], v[30:33]
	v_mfma_f32_16x16x32_bf16 v[22:25], v[152:155], v[208:211], v[22:25]
	v_mfma_f32_16x16x32_bf16 v[14:17], v[140:143], v[216:219], v[14:17]
	v_mfma_f32_16x16x32_bf16 v[6:9], v[152:155], v[216:219], v[6:9]
	v_mfma_f32_16x16x32_bf16 v[62:65], v[144:147], v[180:183], v[62:65]
	v_mfma_f32_16x16x32_bf16 v[54:57], v[156:159], v[180:183], v[54:57]
	v_mfma_f32_16x16x32_bf16 v[46:49], v[144:147], v[204:207], v[46:49]
	v_mfma_f32_16x16x32_bf16 v[38:41], v[156:159], v[204:207], v[38:41]
	v_mfma_f32_16x16x32_bf16 v[30:33], v[144:147], v[212:215], v[30:33]
	v_mfma_f32_16x16x32_bf16 v[22:25], v[156:159], v[212:215], v[22:25]
	v_mfma_f32_16x16x32_bf16 v[14:17], v[144:147], v[232:235], v[14:17]
	v_mfma_f32_16x16x32_bf16 v[6:9], v[156:159], v[232:235], v[6:9]
	s_setprio 0
	s_setprio 1
	v_mfma_f32_16x16x32_bf16 v[58:61], v[160:163], v[176:179], v[58:61]
	v_mfma_f32_16x16x32_bf16 v[50:53], v[168:171], v[176:179], v[50:53]
	v_mfma_f32_16x16x32_bf16 v[42:45], v[160:163], v[200:203], v[42:45]
	v_mfma_f32_16x16x32_bf16 v[34:37], v[168:171], v[200:203], v[34:37]
	v_mfma_f32_16x16x32_bf16 v[26:29], v[160:163], v[208:211], v[26:29]
	v_mfma_f32_16x16x32_bf16 v[18:21], v[168:171], v[208:211], v[18:21]
	v_mfma_f32_16x16x32_bf16 v[10:13], v[160:163], v[216:219], v[10:13]
	v_mfma_f32_16x16x32_bf16 v[2:5], v[168:171], v[216:219], v[2:5]
	v_mfma_f32_16x16x32_bf16 v[58:61], v[164:167], v[180:183], v[58:61]
	v_mfma_f32_16x16x32_bf16 v[50:53], v[172:175], v[180:183], v[50:53]
	v_mfma_f32_16x16x32_bf16 v[42:45], v[164:167], v[204:207], v[42:45]
	v_mfma_f32_16x16x32_bf16 v[34:37], v[172:175], v[204:207], v[34:37]
	v_mfma_f32_16x16x32_bf16 v[26:29], v[164:167], v[212:215], v[26:29]
	v_mfma_f32_16x16x32_bf16 v[18:21], v[172:175], v[212:215], v[18:21]
	v_mfma_f32_16x16x32_bf16 v[10:13], v[164:167], v[232:235], v[10:13]
	v_mfma_f32_16x16x32_bf16 v[2:5], v[172:175], v[232:235], v[2:5]
	s_setprio 0
	s_barrier
; #define PG8_STAGE(bufoff, gbase, voff) do { _Pragma("unroll") for (int _i = 0; _i < 2; ++_i) \
;         __builtin_amdgcn_global_load_lds((const unsigned*)((const char*)(gbase) + (voff)[_i]), (PG8_LAS unsigned*)(lds + (bufoff) + ldsw + _i * 8192), 16, 0, 0); } while (0)
; #define PG8_LDA(dst, b, h) do { _Pragma("unroll") for (int m = 0; m < 4; ++m) _Pragma("unroll") for (int k = 0; k < 2; ++k) dst[m][k] = *(const PG8_LAS bf16x8*)(lds + PG8_SA(b, h) + aoff + m * 2048 + k * 1024); } while (0)
; #define PG8_LDB(dst, b, h) do { _Pragma("unroll") for (int n = 0; n < 2; ++n) _Pragma("unroll") for (int k = 0; k < 2; ++k) dst[n][k] = *(const PG8_LAS bf16x8*)(lds + PG8_SB(b, h) + boff + n * 2048 + k * 1024); } while (0)
; template <class Epi, class Sched, bool ALIGN_EPI = false, bool SP2 = false>
; __device__ __forceinline__ void gemm_phase(PG8_LAS unsigned char* lds, const Gemm g, const Sched& S, const Epi& E) {
;     ...
;         for (int t = 0; t < nt; t += 2) {
;             const bool last = (t == nt - 2);
;             const char* a1 = cA + (size_t)(t + 1) * kstep;
;             const char* a2 = last ? nA : cA + (size_t)(t + 2) * kstep; const char* b2 = last ? nB : cB + (size_t)(t + 2) * kstep;
;             const char* a3 = a2 + kstep; const char* b3 = b2 + kstep;
;             if (last && has_next) S.a_ready(nxt);
;             if constexpr (SP2) {
;             PG8_LDB(B0, 0, 0); PG8_LDB(B1, 0, 1); PG8_SCHED; PG8_LDA(At, 0, 0); PG8_STAGE(PG8_SA(1, 1), a1 + hstep, voffA);
;             PG8_WAIT_V(8); PG8_WAIT_L(0); PG8_BAR; PG8_MMA(0, 0, At, B0); PG8_MMA(0, 1, At, B1); PG8_BAR; PG8_SCHED;
;             PG8_LDA(At, 0, 1); PG8_STAGE(PG8_SB(0, 0), b2, voffB); PG8_STAGE(PG8_SB(0, 1), b2 + hstep, voffB); PG8_STAGE(PG8_SA(0, 0), a2, voffA);
;             PG8_WAIT_V(8); PG8_WAIT_L(0); PG8_BAR; PG8_MMA(1, 0, At, B0); PG8_MMA(1, 1, At, B1); PG8_BAR; PG8_SCHED;
;             PG8_LDB(B0, 1, 0); PG8_LDB(B1, 1, 1); PG8_SCHED; PG8_LDA(At, 1, 0); PG8_STAGE(PG8_SA(0, 1), a2 + hstep, voffA);
;             PG8_WAIT_V(8); PG8_WAIT_L(0); PG8_BAR; PG8_MMA(0, 0, At, B0); PG8_MMA(0, 1, At, B1); PG8_BAR; PG8_SCHED;
;             PG8_LDA(At, 1, 1); PG8_STAGE(PG8_SB(1, 0), b3, voffB); PG8_STAGE(PG8_SB(1, 1), b3 + hstep, voffB); PG8_STAGE(PG8_SA(1, 0), a3, voffA);
;             PG8_WAIT_V(8); PG8_WAIT_L(0); PG8_BAR; PG8_MMA(1, 0, At, B0); PG8_MMA(1, 1, At, B1); PG8_BAR; PG8_SCHED;
	s_add_i32 s58, 0, 0x18000
	s_add_i32 s59, 0, 0x1c000
	v_add_u32_e32 v156, s58, v149
	v_add_u32_e32 v172, s59, v149
	ds_read_b128 v[140:143], v156
	ds_read_b128 v[144:147], v156 offset:1024
	ds_read_b128 v[152:155], v156 offset:2048
	ds_read_b128 v[156:159], v156 offset:3072
	ds_read_b128 v[160:163], v172
	ds_read_b128 v[164:167], v172 offset:1024
	ds_read_b128 v[168:171], v172 offset:2048
	ds_read_b128 v[172:175], v172 offset:3072
	s_add_u32 s2, s50, 0x80000
	s_addc_u32 s3, s51, 0
	s_mov_b32 m0, s37
	ds_read_b128 v[176:179], v151 offset:32768
	ds_read_b128 v[180:183], v151 offset:33792
	ds_read_b128 v[200:203], v151 offset:34816
	ds_read_b128 v[204:207], v151 offset:35840
	ds_read_b128 v[208:211], v151 offset:36864
	ds_read_b128 v[212:215], v151 offset:37888
	ds_read_b128 v[216:219], v151 offset:38912
	ds_read_b128 v[232:235], v151 offset:39936
	global_load_lds_dwordx4 v134, s[2:3]
	s_mov_b32 m0, s38
	s_nop 0
	global_load_lds_dwordx4 v132, s[2:3]
	s_waitcnt vmcnt(8)
	s_waitcnt lgkmcnt(0)
	s_barrier
	s_setprio 1
	s_waitcnt lgkmcnt(0)
	v_mfma_f32_16x16x32_bf16 v[126:129], v[140:143], v[176:179], v[126:129]
	v_mfma_f32_16x16x32_bf16 v[118:121], v[152:155], v[176:179], v[118:121]
	v_mfma_f32_16x16x32_bf16 v[110:113], v[140:143], v[200:203], v[110:113]
	v_mfma_f32_16x16x32_bf16 v[102:105], v[152:155], v[200:203], v[102:105]
	v_mfma_f32_16x16x32_bf16 v[94:97], v[140:143], v[208:211], v[94:97]
	v_mfma_f32_16x16x32_bf16 v[86:89], v[152:155], v[208:211], v[86:89]
	v_mfma_f32_16x16x32_bf16 v[78:81], v[140:143], v[216:219], v[78:81]
	v_mfma_f32_16x16x32_bf16 v[70:73], v[152:155], v[216:219], v[70:73]
	v_mfma_f32_16x16x32_bf16 v[126:129], v[144:147], v[180:183], v[126:129]
	v_mfma_f32_16x16x32_bf16 v[118:121], v[156:159], v[180:183], v[118:121]
	v_mfma_f32_16x16x32_bf16 v[110:113], v[144:147], v[204:207], v[110:113]
	v_mfma_f32_16x16x32_bf16 v[102:105], v[156:159], v[204:207], v[102:105]
	v_mfma_f32_16x16x32_bf16 v[94:97], v[144:147], v[212:215], v[94:97]
	v_mfma_f32_16x16x32_bf16 v[86:89], v[156:159], v[212:215], v[86:89]
	v_mfma_f32_16x16x32_bf16 v[78:81], v[144:147], v[232:235], v[78:81]
	v_mfma_f32_16x16x32_bf16 v[70:73], v[156:159], v[232:235], v[70:73]
	s_setprio 0
	s_setprio 1
	v_mfma_f32_16x16x32_bf16 v[122:125], v[160:163], v[176:179], v[122:125]
	v_mfma_f32_16x16x32_bf16 v[114:117], v[168:171], v[176:179], v[114:117]
	v_mfma_f32_16x16x32_bf16 v[106:109], v[160:163], v[200:203], v[106:109]
	v_mfma_f32_16x16x32_bf16 v[98:101], v[168:171], v[200:203], v[98:101]
	v_mfma_f32_16x16x32_bf16 v[90:93], v[160:163], v[208:211], v[90:93]
	v_mfma_f32_16x16x32_bf16 v[82:85], v[168:171], v[208:211], v[82:85]
	v_mfma_f32_16x16x32_bf16 v[74:77], v[160:163], v[216:219], v[74:77]
	v_mfma_f32_16x16x32_bf16 v[66:69], v[168:171], v[216:219], v[66:69]
	v_mfma_f32_16x16x32_bf16 v[122:125], v[164:167], v[180:183], v[122:125]
	v_mfma_f32_16x16x32_bf16 v[114:117], v[172:175], v[180:183], v[114:117]
	v_mfma_f32_16x16x32_bf16 v[106:109], v[164:167], v[204:207], v[106:109]
	v_mfma_f32_16x16x32_bf16 v[98:101], v[172:175], v[204:207], v[98:101]
	v_mfma_f32_16x16x32_bf16 v[90:93], v[164:167], v[212:215], v[90:93]
	v_mfma_f32_16x16x32_bf16 v[82:85], v[172:175], v[212:215], v[82:85]
	v_mfma_f32_16x16x32_bf16 v[74:77], v[164:167], v[232:235], v[74:77]
	v_mfma_f32_16x16x32_bf16 v[66:69], v[172:175], v[232:235], v[66:69]
	s_setprio 0
	s_barrier
	s_add_u32 s100, s22, 0x80
	s_addc_u32 s101, s23, 0
	s_add_i32 s2, s58, s28
	s_mov_b32 m0, s2
	ds_read_b128 v[176:179], v151 offset:49152
	ds_read_b128 v[180:183], v151 offset:50176
	ds_read_b128 v[200:203], v151 offset:51200
	ds_read_b128 v[204:207], v151 offset:52224
	ds_read_b128 v[208:211], v151 offset:53248
	ds_read_b128 v[212:215], v151 offset:54272
	ds_read_b128 v[216:219], v151 offset:55296
	ds_read_b128 v[232:235], v151 offset:56320
	global_load_lds_dwordx4 v0, s[100:101]
	s_add_i32 m0, s2, 0x2000
	s_add_u32 s2, s22, 0x80080
	s_addc_u32 s3, s23, 0
	s_add_i32 s22, s59, s28
	global_load_lds_dwordx4 v130, s[100:101]
	s_mov_b32 m0, s22
	s_nop 0
	global_load_lds_dwordx4 v0, s[2:3]
	s_add_i32 m0, s22, 0x2000
	s_nop 0
	global_load_lds_dwordx4 v130, s[2:3]
	s_add_u32 s100, s50, 0x80
	s_addc_u32 s101, s51, 0
	s_mov_b32 m0, s47
	s_nop 0
	global_load_lds_dwordx4 v134, s[100:101]
	s_mov_b32 m0, s52
	s_nop 0
	global_load_lds_dwordx4 v132, s[100:101]
	s_waitcnt vmcnt(8)
	s_waitcnt lgkmcnt(0)
	s_barrier
	s_setprio 1
	s_waitcnt lgkmcnt(0)
	v_mfma_f32_16x16x32_bf16 v[62:65], v[140:143], v[176:179], v[62:65]
	v_mfma_f32_16x16x32_bf16 v[54:57], v[152:155], v[176:179], v[54:57]
	v_mfma_f32_16x16x32_bf16 v[46:49], v[140:143], v[200:203], v[46:49]
	v_mfma_f32_16x16x32_bf16 v[38:41], v[152:155], v[200:203], v[38:41]
	v_mfma_f32_16x16x32_bf16 v[30:33], v[140:143], v[208:211], v[30:33]
	v_mfma_f32_16x16x32_bf16 v[22:25], v[152:155], v[208:211], v[22:25]
	v_mfma_f32_16x16x32_bf16 v[14:17], v[140:143], v[216:219], v[14:17]
	v_mfma_f32_16x16x32_bf16 v[6:9], v[152:155], v[216:219], v[6:9]
	v_mfma_f32_16x16x32_bf16 v[62:65], v[144:147], v[180:183], v[62:65]
	v_mfma_f32_16x16x32_bf16 v[54:57], v[156:159], v[180:183], v[54:57]
	v_mfma_f32_16x16x32_bf16 v[46:49], v[144:147], v[204:207], v[46:49]
	v_mfma_f32_16x16x32_bf16 v[38:41], v[156:159], v[204:207], v[38:41]
	v_mfma_f32_16x16x32_bf16 v[30:33], v[144:147], v[212:215], v[30:33]
	v_mfma_f32_16x16x32_bf16 v[22:25], v[156:159], v[212:215], v[22:25]
	v_mfma_f32_16x16x32_bf16 v[14:17], v[144:147], v[232:235], v[14:17]
	v_mfma_f32_16x16x32_bf16 v[6:9], v[156:159], v[232:235], v[6:9]
	s_setprio 0
	s_setprio 1
	v_mfma_f32_16x16x32_bf16 v[58:61], v[160:163], v[176:179], v[58:61]
	v_mfma_f32_16x16x32_bf16 v[50:53], v[168:171], v[176:179], v[50:53]
	v_mfma_f32_16x16x32_bf16 v[42:45], v[160:163], v[200:203], v[42:45]
	v_mfma_f32_16x16x32_bf16 v[34:37], v[168:171], v[200:203], v[34:37]
	v_mfma_f32_16x16x32_bf16 v[26:29], v[160:163], v[208:211], v[26:29]
	v_mfma_f32_16x16x32_bf16 v[18:21], v[168:171], v[208:211], v[18:21]
	v_mfma_f32_16x16x32_bf16 v[10:13], v[160:163], v[216:219], v[10:13]
	v_mfma_f32_16x16x32_bf16 v[2:5], v[168:171], v[216:219], v[2:5]
	v_mfma_f32_16x16x32_bf16 v[58:61], v[164:167], v[180:183], v[58:61]
	v_mfma_f32_16x16x32_bf16 v[50:53], v[172:175], v[180:183], v[50:53]
	v_mfma_f32_16x16x32_bf16 v[42:45], v[164:167], v[204:207], v[42:45]
	v_mfma_f32_16x16x32_bf16 v[34:37], v[172:175], v[204:207], v[34:37]
	v_mfma_f32_16x16x32_bf16 v[26:29], v[164:167], v[212:215], v[26:29]
	v_mfma_f32_16x16x32_bf16 v[18:21], v[172:175], v[212:215], v[18:21]
	v_mfma_f32_16x16x32_bf16 v[10:13], v[164:167], v[232:235], v[10:13]
	v_mfma_f32_16x16x32_bf16 v[2:5], v[172:175], v[232:235], v[2:5]
	s_setprio 0
	s_barrier
	s_add_i32 s57, s57, 2
	s_add_u32 s55, s55, 0x100
	s_addc_u32 s56, s56, 0
	s_add_u32 s48, s48, 0x100
	s_addc_u32 s49, s49, 0
	s_cmp_gt_u32 s57, 29
	s_cbranch_scc0 .LBB0_1487
	s_and_b64 vcc, exec, s[16:17]
	s_cbranch_vccz .LBB0_1490
	s_barrier
